# grid barrier: non-leader workgroups issue their L1/L2 invalidate right after arriving (before polling) instead of after the release
# speedup vs baseline: 1.0124x; 1.0092x over previous
; __device__ __forceinline__ unsigned xb_ld(unsigned* p)              { return __hip_atomic_load(p, __ATOMIC_RELAXED, __HIP_MEMORY_SCOPE_AGENT); }
; __device__ __forceinline__ unsigned xb_add(unsigned* p, unsigned v) { return __hip_atomic_fetch_add(p, v, __ATOMIC_RELAXED, __HIP_MEMORY_SCOPE_AGENT); }
; #define XB_SPIN(cond, bar) do { unsigned _sp = 0; while (cond) { __builtin_amdgcn_s_sleep(1); \
;     if ((++_sp & 255u) == 0u) { if (xb_ld(&(bar)[XB_TMO])) break; if (_sp > XB_SPIN_CAP) { atomicAdd(&(bar)[XB_TMO], 1u); break; } } } } while (0)
; template <bool FLUSH> __device__ __forceinline__ void xcd_barrier(const XcdBarrier& b) {
;     ...
;         const unsigned old = xb_add(&bar[XB_XSUB(b.x)], 1u);
;         const unsigned gen = old / nloc;
;         if (old + 1u == (gen + 1u) * nloc) {
;             if (FLUSH) __builtin_amdgcn_fence(__ATOMIC_RELEASE, "agent");
;             asm volatile("s_waitcnt vmcnt(0)" ::: "memory");
;             const unsigned og = xb_add(&bar[XB_TOP], 1u);
;             const unsigned tg = og / nx;
;             if (og + 1u == (tg + 1u) * nx) xb_add(&bar[XB_TOPGEN], 1u);
;             else XB_SPIN(xb_ld(&bar[XB_TOPGEN]) == tg, bar);
;             __builtin_amdgcn_fence(__ATOMIC_ACQUIRE, "agent");
;             xb_add(&bar[XB_XGEN(b.x)], 1u);
;             asm volatile("s_waitcnt vmcnt(0)" ::: "memory");
;         } else {
;             XB_SPIN(xb_ld(&bar[XB_XGEN(b.x)]) == gen, bar);
;             __builtin_amdgcn_fence(__ATOMIC_ACQUIRE, "agent");
;             asm volatile("s_waitcnt vmcnt(0)" ::: "memory");
.LBB0_87:
	s_lshl_b32 s4, s68, 8
	s_add_u32 s4, s42, s4
	s_addc_u32 s5, s43, 0
	v_mov_b32_e32 v1, 0x1000
	v_mov_b32_e32 v3, 1
	global_atomic_add v3, v1, v3, s[4:5] offset:1024 sc0
	v_cvt_f32_u32_e32 v1, v2
	v_sub_u32_e32 v4, 0, v2
	v_rcp_iflag_f32_e32 v1, v1
	s_nop 0
	v_mul_f32_e32 v1, 0x4f7ffffe, v1
	v_cvt_u32_f32_e32 v1, v1
	v_mul_lo_u32 v4, v4, v1
	v_mul_hi_u32 v4, v1, v4
	v_add_u32_e32 v1, v1, v4
	s_waitcnt vmcnt(0)
	v_mul_hi_u32 v1, v3, v1
	v_mul_lo_u32 v4, v1, v2
	v_sub_u32_e32 v4, v3, v4
	v_add_u32_e32 v5, 1, v1
	v_cmp_ge_u32_e32 vcc, v4, v2
	v_add_u32_e32 v3, 1, v3
	s_nop 0
	v_cndmask_b32_e32 v1, v1, v5, vcc
	v_sub_u32_e32 v5, v4, v2
	v_cndmask_b32_e32 v4, v4, v5, vcc
	v_add_u32_e32 v5, 1, v1
	v_cmp_ge_u32_e32 vcc, v4, v2
	s_nop 1
	v_cndmask_b32_e32 v1, v1, v5, vcc
	v_mul_lo_u32 v4, v2, v1
	v_add_u32_e32 v2, v4, v2
	v_cmp_ne_u32_e32 vcc, v3, v2
	s_and_saveexec_b64 s[6:7], vcc
	s_xor_b64 s[6:7], exec, s[6:7]
	s_cbranch_execz .LBB0_100
	s_waitcnt lgkmcnt(0)
	buffer_inv sc1
	v_mov_b32_e32 v0, 0x2000
	global_load_dword v0, v0, s[4:5] offset:1024 sc1
	s_add_u32 s10, s4, 0x2400
	s_addc_u32 s11, s5, 0
	s_waitcnt vmcnt(0)
	v_cmp_eq_u32_e32 vcc, v0, v1
	s_and_saveexec_b64 s[8:9], vcc
	s_cbranch_execz .LBB0_99
	s_mov_b32 s22, 1
	s_mov_b64 s[12:13], 0
	v_mov_b32_e32 v0, 0
	s_branch .LBB0_91

; __device__ __forceinline__ unsigned xb_ld(unsigned* p)              { return __hip_atomic_load(p, __ATOMIC_RELAXED, __HIP_MEMORY_SCOPE_AGENT); }
; #define XB_SPIN(cond, bar) do { unsigned _sp = 0; while (cond) { __builtin_amdgcn_s_sleep(1); \
;     if ((++_sp & 255u) == 0u) { if (xb_ld(&(bar)[XB_TMO])) break; if (_sp > XB_SPIN_CAP) { atomicAdd(&(bar)[XB_TMO], 1u); break; } } } } while (0)
; template <bool FLUSH> __device__ __forceinline__ void xcd_barrier(const XcdBarrier& b) {
;     ...
;         } else {
;             XB_SPIN(xb_ld(&bar[XB_XGEN(b.x)]) == gen, bar);
;             __builtin_amdgcn_fence(__ATOMIC_ACQUIRE, "agent");
;             asm volatile("s_waitcnt vmcnt(0)" ::: "memory");
;         }
.LBB0_99:
	s_or_b64 exec, exec, s[8:9]
	s_waitcnt vmcnt(0)
	s_waitcnt vmcnt(0)

; __device__ __forceinline__ unsigned xb_ld(unsigned* p)              { return __hip_atomic_load(p, __ATOMIC_RELAXED, __HIP_MEMORY_SCOPE_AGENT); }
; __device__ __forceinline__ unsigned xb_add(unsigned* p, unsigned v) { return __hip_atomic_fetch_add(p, v, __ATOMIC_RELAXED, __HIP_MEMORY_SCOPE_AGENT); }
; #define XB_SPIN(cond, bar) do { unsigned _sp = 0; while (cond) { __builtin_amdgcn_s_sleep(1); \
;     if ((++_sp & 255u) == 0u) { if (xb_ld(&(bar)[XB_TMO])) break; if (_sp > XB_SPIN_CAP) { atomicAdd(&(bar)[XB_TMO], 1u); break; } } } } while (0)
; template <bool FLUSH> __device__ __forceinline__ void xcd_barrier(const XcdBarrier& b) {
;     ...
;         const unsigned old = xb_add(&bar[XB_XSUB(b.x)], 1u);
;         const unsigned gen = old / nloc;
;         if (old + 1u == (gen + 1u) * nloc) {
;             if (FLUSH) __builtin_amdgcn_fence(__ATOMIC_RELEASE, "agent");
;             asm volatile("s_waitcnt vmcnt(0)" ::: "memory");
;             const unsigned og = xb_add(&bar[XB_TOP], 1u);
;             const unsigned tg = og / nx;
;             if (og + 1u == (tg + 1u) * nx) xb_add(&bar[XB_TOPGEN], 1u);
;             else XB_SPIN(xb_ld(&bar[XB_TOPGEN]) == tg, bar);
;             __builtin_amdgcn_fence(__ATOMIC_ACQUIRE, "agent");
;             xb_add(&bar[XB_XGEN(b.x)], 1u);
;             asm volatile("s_waitcnt vmcnt(0)" ::: "memory");
;         } else {
;             XB_SPIN(xb_ld(&bar[XB_XGEN(b.x)]) == gen, bar);
;             __builtin_amdgcn_fence(__ATOMIC_ACQUIRE, "agent");
;             asm volatile("s_waitcnt vmcnt(0)" ::: "memory");
.LBB0_2199:
	s_lshl_b32 s2, s68, 8
	s_add_u32 s2, s42, s2
	s_addc_u32 s3, s43, 0
	v_mov_b32_e32 v1, 0x1000
	v_mov_b32_e32 v3, 1
	global_atomic_add v3, v1, v3, s[2:3] offset:1024 sc0
	v_cvt_f32_u32_e32 v1, v2
	v_sub_u32_e32 v4, 0, v2
	v_rcp_iflag_f32_e32 v1, v1
	s_nop 0
	v_mul_f32_e32 v1, 0x4f7ffffe, v1
	v_cvt_u32_f32_e32 v1, v1
	v_mul_lo_u32 v4, v4, v1
	v_mul_hi_u32 v4, v1, v4
	v_add_u32_e32 v1, v1, v4
	s_waitcnt vmcnt(0)
	v_mul_hi_u32 v1, v3, v1
	v_mul_lo_u32 v4, v1, v2
	v_sub_u32_e32 v4, v3, v4
	v_add_u32_e32 v5, 1, v1
	v_cmp_ge_u32_e32 vcc, v4, v2
	v_add_u32_e32 v3, 1, v3
	s_nop 0
	v_cndmask_b32_e32 v1, v1, v5, vcc
	v_sub_u32_e32 v5, v4, v2
	v_cndmask_b32_e32 v4, v4, v5, vcc
	v_add_u32_e32 v5, 1, v1
	v_cmp_ge_u32_e32 vcc, v4, v2
	s_nop 1
	v_cndmask_b32_e32 v1, v1, v5, vcc
	v_mul_lo_u32 v4, v2, v1
	v_add_u32_e32 v2, v4, v2
	v_cmp_ne_u32_e32 vcc, v3, v2
	s_and_saveexec_b64 s[4:5], vcc
	s_xor_b64 s[4:5], exec, s[4:5]
	s_cbranch_execz .LBB0_2212
	s_waitcnt lgkmcnt(0)
	buffer_inv sc1
	v_mov_b32_e32 v0, 0x2000
	global_load_dword v0, v0, s[2:3] offset:1024 sc1
	s_add_u32 s8, s2, 0x2400
	s_addc_u32 s9, s3, 0
	s_waitcnt vmcnt(0)
	v_cmp_eq_u32_e32 vcc, v0, v1
	s_and_saveexec_b64 s[6:7], vcc
	s_cbranch_execz .LBB0_2211
	s_mov_b32 s20, 1
	s_mov_b64 s[10:11], 0
	v_mov_b32_e32 v0, 0
	s_branch .LBB0_2203

; __device__ __forceinline__ unsigned xb_ld(unsigned* p)              { return __hip_atomic_load(p, __ATOMIC_RELAXED, __HIP_MEMORY_SCOPE_AGENT); }
; #define XB_SPIN(cond, bar) do { unsigned _sp = 0; while (cond) { __builtin_amdgcn_s_sleep(1); \
;     if ((++_sp & 255u) == 0u) { if (xb_ld(&(bar)[XB_TMO])) break; if (_sp > XB_SPIN_CAP) { atomicAdd(&(bar)[XB_TMO], 1u); break; } } } } while (0)
; template <bool FLUSH> __device__ __forceinline__ void xcd_barrier(const XcdBarrier& b) {
;     ...
;         } else {
;             XB_SPIN(xb_ld(&bar[XB_XGEN(b.x)]) == gen, bar);
;             __builtin_amdgcn_fence(__ATOMIC_ACQUIRE, "agent");
;             asm volatile("s_waitcnt vmcnt(0)" ::: "memory");
;         }
.LBB0_2211:
	s_or_b64 exec, exec, s[6:7]
	s_waitcnt vmcnt(0)
	s_waitcnt vmcnt(0)
